# prep gain/W_IN items: both 8-row halves unrolled, second half's row loads issued as each first-half row is consumed, all 16 gains loaded up front
# speedup vs baseline: 1.0037x; 1.0037x over previous
; #define LAS __attribute__((address_space(3)))
;     if (ldk == 0) ldk = K;
;     const int c4 = lane & 15, kr = lane >> 4;
; #pragma unroll 8
;     for (int i = 0; i < 16; ++i) { const int kk = 4 * i + kr; const float gs = gain ? gain[k0 + kk] : 1.f; const f32x4 v = *(const f32x4*)(W + (size_t)(k0 + kk) * N + n0 + 4 * c4); *(LAS f32x4*)(scr + kk * 68 + 4 * c4) = v * gs; }
;     asm volatile("s_waitcnt lgkmcnt(0)" ::: "memory");
; __device__ __forceinline__ void tr_gu(const float* W, bf16_t* WT, const float* gain, int up, int item, LAS float* scr, int lane) {
;     const int nblk = DFF / 64, kb = item / nblk, nb = item % nblk, n0 = nb * 64;
;     transpose_item(W, DFF, DM, WT, gain, (n0 >> 7) * 256 + (n0 & 127) + up * 128, kb * 64, n0, scr, lane);
; }
.LBB0_341:
	v_cndmask_b32_e64 v128, 0, 1, s[82:83]
	v_mov_b32_e32 v106, 1.0
	v_mov_b32_e32 v108, 1.0
	v_mov_b32_e32 v110, 1.0
	v_mov_b32_e32 v112, 1.0
	v_mov_b32_e32 v114, 1.0
	v_mov_b32_e32 v116, 1.0
	v_mov_b32_e32 v118, 1.0
	v_mov_b32_e32 v120, 1.0
	v_mov_b32_e32 v122, 1.0
	v_mov_b32_e32 v124, 1.0
	v_mov_b32_e32 v126, 1.0
	v_mov_b32_e32 v240, 1.0
	v_mov_b32_e32 v242, 1.0
	v_mov_b32_e32 v244, 1.0
	v_mov_b32_e32 v246, 1.0
	v_mov_b32_e32 v248, 1.0
	v_cmp_ne_u32_e64 s[40:41], 1, v128
	s_andn2_b64 vcc, exec, s[82:83]
	s_cbranch_vccnz .Lpw_ng_341
	v_lshl_add_u64 v[172:173], v[52:53], 0, s[46:47]
	global_load_dword v106, v[172:173], off
	v_lshl_add_u64 v[138:139], v[36:37], 0, s[46:47]
	global_load_dword v108, v[138:139], off offset:16
	global_load_dword v110, v[138:139], off offset:32
	global_load_dword v112, v[138:139], off offset:48
	global_load_dword v114, v[138:139], off offset:64
	global_load_dword v116, v[138:139], off offset:80
	global_load_dword v118, v[138:139], off offset:96
	global_load_dword v120, v[138:139], off offset:112
	v_lshl_add_u64 v[172:173], v[172:173], 0, s[34:35]
	global_load_dword v122, v[172:173], off
	v_lshl_add_u64 v[138:139], v[138:139], 0, s[34:35]
	global_load_dword v124, v[138:139], off offset:16
	global_load_dword v126, v[138:139], off offset:32
	global_load_dword v240, v[138:139], off offset:48
	global_load_dword v242, v[138:139], off offset:64
	global_load_dword v244, v[138:139], off offset:80
	global_load_dword v246, v[138:139], off offset:96
	global_load_dword v248, v[138:139], off offset:112
.Lpw_ng_341:
	v_lshl_add_u64 v[140:141], v[50:51], 0, s[80:81]
	global_load_dwordx4 v[140:143], v[140:141], off
	v_lshl_add_u64 v[144:145], v[48:49], 0, s[80:81]
	global_load_dwordx4 v[144:147], v[144:145], off
	v_lshl_add_u64 v[148:149], v[46:47], 0, s[80:81]
	global_load_dwordx4 v[148:151], v[148:149], off
	v_lshl_add_u64 v[152:153], v[44:45], 0, s[80:81]
	global_load_dwordx4 v[152:155], v[152:153], off
	v_lshl_add_u64 v[156:157], v[42:43], 0, s[80:81]
	global_load_dwordx4 v[156:159], v[156:157], off
	v_lshl_add_u64 v[160:161], v[40:41], 0, s[80:81]
	global_load_dwordx4 v[160:163], v[160:161], off
	v_lshl_add_u64 v[164:165], v[38:39], 0, s[80:81]
	global_load_dwordx4 v[164:167], v[164:165], off
	v_lshl_add_u64 v[168:169], v[34:35], 0, s[80:81]
	global_load_dwordx4 v[168:171], v[168:169], off
	s_add_u32 s80, s80, 0x58000
	s_addc_u32 s81, s81, 0
	v_lshl_add_u64 v[36:37], v[36:37], 0, s[34:35]
	v_lshl_add_u64 v[52:53], v[52:53], 0, s[34:35]
	v_lshl_add_u64 v[36:37], v[36:37], 0, s[34:35]
	v_lshl_add_u64 v[52:53], v[52:53], 0, s[34:35]
	s_waitcnt vmcnt(7)
	v_pk_mul_f32 v[140:141], v[140:141], v[106:107] op_sel_hi:[1,0]
	v_pk_mul_f32 v[142:143], v[142:143], v[106:107] op_sel_hi:[1,0]
	ds_write_b128 v60, v[140:143] offset:0
	v_lshl_add_u64 v[172:173], v[50:51], 0, s[80:81]
	global_load_dwordx4 v[140:143], v[172:173], off
	s_waitcnt vmcnt(7)
	v_pk_mul_f32 v[144:145], v[144:145], v[108:109] op_sel_hi:[1,0]
	v_pk_mul_f32 v[146:147], v[146:147], v[108:109] op_sel_hi:[1,0]
	ds_write_b128 v60, v[144:147] offset:1088
	v_lshl_add_u64 v[138:139], v[48:49], 0, s[80:81]
	global_load_dwordx4 v[144:147], v[138:139], off
	s_waitcnt vmcnt(7)
	v_pk_mul_f32 v[148:149], v[148:149], v[110:111] op_sel_hi:[1,0]
	v_pk_mul_f32 v[150:151], v[150:151], v[110:111] op_sel_hi:[1,0]
	ds_write_b128 v60, v[148:151] offset:2176
	v_lshl_add_u64 v[172:173], v[46:47], 0, s[80:81]
	global_load_dwordx4 v[148:151], v[172:173], off
	s_waitcnt vmcnt(7)
	v_pk_mul_f32 v[152:153], v[152:153], v[112:113] op_sel_hi:[1,0]
	v_pk_mul_f32 v[154:155], v[154:155], v[112:113] op_sel_hi:[1,0]
	ds_write_b128 v60, v[152:155] offset:3264
	v_lshl_add_u64 v[138:139], v[44:45], 0, s[80:81]
	global_load_dwordx4 v[152:155], v[138:139], off
	s_waitcnt vmcnt(7)
	v_pk_mul_f32 v[156:157], v[156:157], v[114:115] op_sel_hi:[1,0]
	v_pk_mul_f32 v[158:159], v[158:159], v[114:115] op_sel_hi:[1,0]
	ds_write_b128 v60, v[156:159] offset:4352
	v_lshl_add_u64 v[172:173], v[42:43], 0, s[80:81]
	global_load_dwordx4 v[156:159], v[172:173], off
	s_waitcnt vmcnt(7)
	v_pk_mul_f32 v[160:161], v[160:161], v[116:117] op_sel_hi:[1,0]
	v_pk_mul_f32 v[162:163], v[162:163], v[116:117] op_sel_hi:[1,0]
	ds_write_b128 v60, v[160:163] offset:5440
	v_lshl_add_u64 v[138:139], v[40:41], 0, s[80:81]
	global_load_dwordx4 v[160:163], v[138:139], off
	s_waitcnt vmcnt(7)
	v_pk_mul_f32 v[164:165], v[164:165], v[118:119] op_sel_hi:[1,0]
	v_pk_mul_f32 v[166:167], v[166:167], v[118:119] op_sel_hi:[1,0]
	ds_write_b128 v60, v[164:167] offset:6528
	v_lshl_add_u64 v[172:173], v[38:39], 0, s[80:81]
	global_load_dwordx4 v[164:167], v[172:173], off
	s_waitcnt vmcnt(7)
	v_pk_mul_f32 v[168:169], v[168:169], v[120:121] op_sel_hi:[1,0]
	v_pk_mul_f32 v[170:171], v[170:171], v[120:121] op_sel_hi:[1,0]
	ds_write_b128 v60, v[168:171] offset:7616
	v_lshl_add_u64 v[138:139], v[34:35], 0, s[80:81]
	global_load_dwordx4 v[168:171], v[138:139], off
	s_add_u32 s80, s80, 0x58000
	s_addc_u32 s81, s81, 0
	s_waitcnt vmcnt(7)
	v_pk_mul_f32 v[140:141], v[140:141], v[122:123] op_sel_hi:[1,0]
	v_pk_mul_f32 v[142:143], v[142:143], v[122:123] op_sel_hi:[1,0]
	ds_write_b128 v60, v[140:143] offset:8704
	s_waitcnt vmcnt(6)
	v_pk_mul_f32 v[144:145], v[144:145], v[124:125] op_sel_hi:[1,0]
	v_pk_mul_f32 v[146:147], v[146:147], v[124:125] op_sel_hi:[1,0]
	ds_write_b128 v60, v[144:147] offset:9792
	s_waitcnt vmcnt(5)
	v_pk_mul_f32 v[148:149], v[148:149], v[126:127] op_sel_hi:[1,0]
	v_pk_mul_f32 v[150:151], v[150:151], v[126:127] op_sel_hi:[1,0]
	ds_write_b128 v60, v[148:151] offset:10880
	s_waitcnt vmcnt(4)
	v_pk_mul_f32 v[152:153], v[152:153], v[240:241] op_sel_hi:[1,0]
	v_pk_mul_f32 v[154:155], v[154:155], v[240:241] op_sel_hi:[1,0]
	ds_write_b128 v60, v[152:155] offset:11968
	s_waitcnt vmcnt(3)
	v_pk_mul_f32 v[156:157], v[156:157], v[242:243] op_sel_hi:[1,0]
	v_pk_mul_f32 v[158:159], v[158:159], v[242:243] op_sel_hi:[1,0]
	ds_write_b128 v60, v[156:159] offset:13056
	s_waitcnt vmcnt(2)
	v_pk_mul_f32 v[160:161], v[160:161], v[244:245] op_sel_hi:[1,0]
	v_pk_mul_f32 v[162:163], v[162:163], v[244:245] op_sel_hi:[1,0]
	ds_write_b128 v60, v[160:163] offset:14144
	s_waitcnt vmcnt(1)
	v_pk_mul_f32 v[164:165], v[164:165], v[246:247] op_sel_hi:[1,0]
	v_pk_mul_f32 v[166:167], v[166:167], v[246:247] op_sel_hi:[1,0]
	ds_write_b128 v60, v[164:167] offset:15232
	s_waitcnt vmcnt(0)
	v_pk_mul_f32 v[168:169], v[168:169], v[248:249] op_sel_hi:[1,0]
	v_pk_mul_f32 v[170:171], v[170:171], v[248:249] op_sel_hi:[1,0]
	ds_write_b128 v60, v[168:171] offset:16320
	v_add_u32_e32 v60, 0x4400, v60
	s_cmp_lg_u32 s80, 0xb0000
	s_branch .LBB0_357

; #define LAS __attribute__((address_space(3)))
;     if (ldk == 0) ldk = K;
;     const int c4 = lane & 15, kr = lane >> 4;
; #pragma unroll 8
;     for (int i = 0; i < 16; ++i) { const int kk = 4 * i + kr; const float gs = gain ? gain[k0 + kk] : 1.f; const f32x4 v = *(const f32x4*)(W + (size_t)(k0 + kk) * N + n0 + 4 * c4); *(LAS f32x4*)(scr + kk * 68 + 4 * c4) = v * gs; }
;     asm volatile("s_waitcnt lgkmcnt(0)" ::: "memory");
;     const int nblk = N / 64, kb = item / nblk, nb = item % nblk;
;     transpose_item(W, N, K, WT, gain, nb * 64, kb * 64, nb * 64, scr, lane, ldk, koff);
; }
.LBB0_403:
	v_cndmask_b32_e64 v128, 0, 1, s[72:73]
	v_mov_b32_e32 v106, 1.0
	v_mov_b32_e32 v108, 1.0
	v_mov_b32_e32 v110, 1.0
	v_mov_b32_e32 v112, 1.0
	v_mov_b32_e32 v114, 1.0
	v_mov_b32_e32 v116, 1.0
	v_mov_b32_e32 v118, 1.0
	v_mov_b32_e32 v120, 1.0
	v_mov_b32_e32 v122, 1.0
	v_mov_b32_e32 v124, 1.0
	v_mov_b32_e32 v126, 1.0
	v_mov_b32_e32 v240, 1.0
	v_mov_b32_e32 v242, 1.0
	v_mov_b32_e32 v244, 1.0
	v_mov_b32_e32 v246, 1.0
	v_mov_b32_e32 v248, 1.0
	v_cmp_ne_u32_e64 s[40:41], 1, v128
	s_andn2_b64 vcc, exec, s[72:73]
	s_cbranch_vccnz .Lpw_ng_403
	v_lshl_add_u64 v[172:173], v[52:53], 0, s[46:47]
	global_load_dword v106, v[172:173], off
	v_lshl_add_u64 v[138:139], v[36:37], 0, s[46:47]
	global_load_dword v108, v[138:139], off offset:16
	global_load_dword v110, v[138:139], off offset:32
	global_load_dword v112, v[138:139], off offset:48
	global_load_dword v114, v[138:139], off offset:64
	global_load_dword v116, v[138:139], off offset:80
	global_load_dword v118, v[138:139], off offset:96
	global_load_dword v120, v[138:139], off offset:112
	v_lshl_add_u64 v[172:173], v[172:173], 0, s[34:35]
	global_load_dword v122, v[172:173], off
	v_lshl_add_u64 v[138:139], v[138:139], 0, s[34:35]
	global_load_dword v124, v[138:139], off offset:16
	global_load_dword v126, v[138:139], off offset:32
	global_load_dword v240, v[138:139], off offset:48
	global_load_dword v242, v[138:139], off offset:64
	global_load_dword v244, v[138:139], off offset:80
	global_load_dword v246, v[138:139], off offset:96
	global_load_dword v248, v[138:139], off offset:112
.Lpw_ng_403:
	v_lshl_add_u64 v[140:141], v[50:51], 0, s[70:71]
	global_load_dwordx4 v[140:143], v[140:141], off
	v_lshl_add_u64 v[144:145], v[48:49], 0, s[70:71]
	global_load_dwordx4 v[144:147], v[144:145], off
	v_lshl_add_u64 v[148:149], v[46:47], 0, s[70:71]
	global_load_dwordx4 v[148:151], v[148:149], off
	v_lshl_add_u64 v[152:153], v[44:45], 0, s[70:71]
	global_load_dwordx4 v[152:155], v[152:153], off
	v_lshl_add_u64 v[156:157], v[42:43], 0, s[70:71]
	global_load_dwordx4 v[156:159], v[156:157], off
	v_lshl_add_u64 v[160:161], v[40:41], 0, s[70:71]
	global_load_dwordx4 v[160:163], v[160:161], off
	v_lshl_add_u64 v[164:165], v[38:39], 0, s[70:71]
	global_load_dwordx4 v[164:167], v[164:165], off
	v_lshl_add_u64 v[168:169], v[34:35], 0, s[70:71]
	global_load_dwordx4 v[168:171], v[168:169], off
	s_add_u32 s70, s70, 0x110000
	s_addc_u32 s71, s71, 0
	v_lshl_add_u64 v[36:37], v[36:37], 0, s[34:35]
	v_lshl_add_u64 v[52:53], v[52:53], 0, s[34:35]
	v_lshl_add_u64 v[36:37], v[36:37], 0, s[34:35]
	v_lshl_add_u64 v[52:53], v[52:53], 0, s[34:35]
	s_waitcnt vmcnt(7)
	v_pk_mul_f32 v[140:141], v[140:141], v[106:107] op_sel_hi:[1,0]
	v_pk_mul_f32 v[142:143], v[142:143], v[106:107] op_sel_hi:[1,0]
	ds_write_b128 v59, v[140:143] offset:0
	v_lshl_add_u64 v[172:173], v[50:51], 0, s[70:71]
	global_load_dwordx4 v[140:143], v[172:173], off
	s_waitcnt vmcnt(7)
	v_pk_mul_f32 v[144:145], v[144:145], v[108:109] op_sel_hi:[1,0]
	v_pk_mul_f32 v[146:147], v[146:147], v[108:109] op_sel_hi:[1,0]
	ds_write_b128 v59, v[144:147] offset:1088
	v_lshl_add_u64 v[138:139], v[48:49], 0, s[70:71]
	global_load_dwordx4 v[144:147], v[138:139], off
	s_waitcnt vmcnt(7)
	v_pk_mul_f32 v[148:149], v[148:149], v[110:111] op_sel_hi:[1,0]
	v_pk_mul_f32 v[150:151], v[150:151], v[110:111] op_sel_hi:[1,0]
	ds_write_b128 v59, v[148:151] offset:2176
	v_lshl_add_u64 v[172:173], v[46:47], 0, s[70:71]
	global_load_dwordx4 v[148:151], v[172:173], off
	s_waitcnt vmcnt(7)
	v_pk_mul_f32 v[152:153], v[152:153], v[112:113] op_sel_hi:[1,0]
	v_pk_mul_f32 v[154:155], v[154:155], v[112:113] op_sel_hi:[1,0]
	ds_write_b128 v59, v[152:155] offset:3264
	v_lshl_add_u64 v[138:139], v[44:45], 0, s[70:71]
	global_load_dwordx4 v[152:155], v[138:139], off
	s_waitcnt vmcnt(7)
	v_pk_mul_f32 v[156:157], v[156:157], v[114:115] op_sel_hi:[1,0]
	v_pk_mul_f32 v[158:159], v[158:159], v[114:115] op_sel_hi:[1,0]
	ds_write_b128 v59, v[156:159] offset:4352
	v_lshl_add_u64 v[172:173], v[42:43], 0, s[70:71]
	global_load_dwordx4 v[156:159], v[172:173], off
	s_waitcnt vmcnt(7)
	v_pk_mul_f32 v[160:161], v[160:161], v[116:117] op_sel_hi:[1,0]
	v_pk_mul_f32 v[162:163], v[162:163], v[116:117] op_sel_hi:[1,0]
	ds_write_b128 v59, v[160:163] offset:5440
	v_lshl_add_u64 v[138:139], v[40:41], 0, s[70:71]
	global_load_dwordx4 v[160:163], v[138:139], off
	s_waitcnt vmcnt(7)
	v_pk_mul_f32 v[164:165], v[164:165], v[118:119] op_sel_hi:[1,0]
	v_pk_mul_f32 v[166:167], v[166:167], v[118:119] op_sel_hi:[1,0]
	ds_write_b128 v59, v[164:167] offset:6528
	v_lshl_add_u64 v[172:173], v[38:39], 0, s[70:71]
	global_load_dwordx4 v[164:167], v[172:173], off
	s_waitcnt vmcnt(7)
	v_pk_mul_f32 v[168:169], v[168:169], v[120:121] op_sel_hi:[1,0]
	v_pk_mul_f32 v[170:171], v[170:171], v[120:121] op_sel_hi:[1,0]
	ds_write_b128 v59, v[168:171] offset:7616
	v_lshl_add_u64 v[138:139], v[34:35], 0, s[70:71]
	global_load_dwordx4 v[168:171], v[138:139], off
	s_add_u32 s70, s70, 0x110000
	s_addc_u32 s71, s71, 0
	s_waitcnt vmcnt(7)
	v_pk_mul_f32 v[140:141], v[140:141], v[122:123] op_sel_hi:[1,0]
	v_pk_mul_f32 v[142:143], v[142:143], v[122:123] op_sel_hi:[1,0]
	ds_write_b128 v59, v[140:143] offset:8704
	s_waitcnt vmcnt(6)
	v_pk_mul_f32 v[144:145], v[144:145], v[124:125] op_sel_hi:[1,0]
	v_pk_mul_f32 v[146:147], v[146:147], v[124:125] op_sel_hi:[1,0]
	ds_write_b128 v59, v[144:147] offset:9792
	s_waitcnt vmcnt(5)
	v_pk_mul_f32 v[148:149], v[148:149], v[126:127] op_sel_hi:[1,0]
	v_pk_mul_f32 v[150:151], v[150:151], v[126:127] op_sel_hi:[1,0]
	ds_write_b128 v59, v[148:151] offset:10880
	s_waitcnt vmcnt(4)
	v_pk_mul_f32 v[152:153], v[152:153], v[240:241] op_sel_hi:[1,0]
	v_pk_mul_f32 v[154:155], v[154:155], v[240:241] op_sel_hi:[1,0]
	ds_write_b128 v59, v[152:155] offset:11968
	s_waitcnt vmcnt(3)
	v_pk_mul_f32 v[156:157], v[156:157], v[242:243] op_sel_hi:[1,0]
	v_pk_mul_f32 v[158:159], v[158:159], v[242:243] op_sel_hi:[1,0]
	ds_write_b128 v59, v[156:159] offset:13056
	s_waitcnt vmcnt(2)
	v_pk_mul_f32 v[160:161], v[160:161], v[244:245] op_sel_hi:[1,0]
	v_pk_mul_f32 v[162:163], v[162:163], v[244:245] op_sel_hi:[1,0]
	ds_write_b128 v59, v[160:163] offset:14144
	s_waitcnt vmcnt(1)
	v_pk_mul_f32 v[164:165], v[164:165], v[246:247] op_sel_hi:[1,0]
	v_pk_mul_f32 v[166:167], v[166:167], v[246:247] op_sel_hi:[1,0]
	ds_write_b128 v59, v[164:167] offset:15232
	s_waitcnt vmcnt(0)
	v_pk_mul_f32 v[168:169], v[168:169], v[248:249] op_sel_hi:[1,0]
	v_pk_mul_f32 v[170:171], v[170:171], v[248:249] op_sel_hi:[1,0]
	ds_write_b128 v59, v[168:171] offset:16320
	v_add_u32_e32 v59, 0x4400, v59
	s_cmp_lg_u32 s70, 0x220000
	s_branch .LBB0_419

; #define LAS __attribute__((address_space(3)))
;     if (ldk == 0) ldk = K;
;     const int c4 = lane & 15, kr = lane >> 4;
; #pragma unroll 8
;     for (int i = 0; i < 16; ++i) { const int kk = 4 * i + kr; const float gs = gain ? gain[k0 + kk] : 1.f; const f32x4 v = *(const f32x4*)(W + (size_t)(k0 + kk) * N + n0 + 4 * c4); *(LAS f32x4*)(scr + kk * 68 + 4 * c4) = v * gs; }
;     asm volatile("s_waitcnt lgkmcnt(0)" ::: "memory");
.LBB0_429:
	v_cndmask_b32_e64 v128, 0, 1, s[56:57]
	v_mov_b32_e32 v106, 1.0
	v_mov_b32_e32 v108, 1.0
	v_mov_b32_e32 v110, 1.0
	v_mov_b32_e32 v112, 1.0
	v_mov_b32_e32 v114, 1.0
	v_mov_b32_e32 v116, 1.0
	v_mov_b32_e32 v118, 1.0
	v_mov_b32_e32 v120, 1.0
	v_mov_b32_e32 v122, 1.0
	v_mov_b32_e32 v124, 1.0
	v_mov_b32_e32 v126, 1.0
	v_mov_b32_e32 v240, 1.0
	v_mov_b32_e32 v242, 1.0
	v_mov_b32_e32 v244, 1.0
	v_mov_b32_e32 v246, 1.0
	v_mov_b32_e32 v248, 1.0
	v_cmp_ne_u32_e64 s[40:41], 1, v128
	s_andn2_b64 vcc, exec, s[56:57]
	s_cbranch_vccnz .Lpw_ng_429
	v_lshl_add_u64 v[172:173], v[52:53], 0, s[46:47]
	global_load_dword v106, v[172:173], off
	v_lshl_add_u64 v[138:139], v[36:37], 0, s[46:47]
	global_load_dword v108, v[138:139], off offset:16
	global_load_dword v110, v[138:139], off offset:32
	global_load_dword v112, v[138:139], off offset:48
	global_load_dword v114, v[138:139], off offset:64
	global_load_dword v116, v[138:139], off offset:80
	global_load_dword v118, v[138:139], off offset:96
	global_load_dword v120, v[138:139], off offset:112
	v_lshl_add_u64 v[172:173], v[172:173], 0, s[34:35]
	global_load_dword v122, v[172:173], off
	v_lshl_add_u64 v[138:139], v[138:139], 0, s[34:35]
	global_load_dword v124, v[138:139], off offset:16
	global_load_dword v126, v[138:139], off offset:32
	global_load_dword v240, v[138:139], off offset:48
	global_load_dword v242, v[138:139], off offset:64
	global_load_dword v244, v[138:139], off offset:80
	global_load_dword v246, v[138:139], off offset:96
	global_load_dword v248, v[138:139], off offset:112
.Lpw_ng_429:
	v_lshl_add_u64 v[140:141], v[50:51], 0, s[54:55]
	global_load_dwordx4 v[140:143], v[140:141], off
	v_lshl_add_u64 v[144:145], v[48:49], 0, s[54:55]
	global_load_dwordx4 v[144:147], v[144:145], off
	v_lshl_add_u64 v[148:149], v[46:47], 0, s[54:55]
	global_load_dwordx4 v[148:151], v[148:149], off
	v_lshl_add_u64 v[152:153], v[44:45], 0, s[54:55]
	global_load_dwordx4 v[152:155], v[152:153], off
	v_lshl_add_u64 v[156:157], v[42:43], 0, s[54:55]
	global_load_dwordx4 v[156:159], v[156:157], off
	v_lshl_add_u64 v[160:161], v[40:41], 0, s[54:55]
	global_load_dwordx4 v[160:163], v[160:161], off
	v_lshl_add_u64 v[164:165], v[38:39], 0, s[54:55]
	global_load_dwordx4 v[164:167], v[164:165], off
	v_lshl_add_u64 v[168:169], v[34:35], 0, s[54:55]
	global_load_dwordx4 v[168:171], v[168:169], off
	s_add_u32 s54, s54, 0x58000
	s_addc_u32 s55, s55, 0
	v_lshl_add_u64 v[36:37], v[36:37], 0, s[34:35]
	v_lshl_add_u64 v[52:53], v[52:53], 0, s[34:35]
	v_lshl_add_u64 v[36:37], v[36:37], 0, s[34:35]
	v_lshl_add_u64 v[52:53], v[52:53], 0, s[34:35]
	s_waitcnt vmcnt(7)
	v_pk_mul_f32 v[140:141], v[140:141], v[106:107] op_sel_hi:[1,0]
	v_pk_mul_f32 v[142:143], v[142:143], v[106:107] op_sel_hi:[1,0]
	ds_write_b128 v60, v[140:143] offset:0
	v_lshl_add_u64 v[172:173], v[50:51], 0, s[54:55]
	global_load_dwordx4 v[140:143], v[172:173], off
	s_waitcnt vmcnt(7)
	v_pk_mul_f32 v[144:145], v[144:145], v[108:109] op_sel_hi:[1,0]
	v_pk_mul_f32 v[146:147], v[146:147], v[108:109] op_sel_hi:[1,0]
	ds_write_b128 v60, v[144:147] offset:1088
	v_lshl_add_u64 v[138:139], v[48:49], 0, s[54:55]
	global_load_dwordx4 v[144:147], v[138:139], off
	s_waitcnt vmcnt(7)
	v_pk_mul_f32 v[148:149], v[148:149], v[110:111] op_sel_hi:[1,0]
	v_pk_mul_f32 v[150:151], v[150:151], v[110:111] op_sel_hi:[1,0]
	ds_write_b128 v60, v[148:151] offset:2176
	v_lshl_add_u64 v[172:173], v[46:47], 0, s[54:55]
	global_load_dwordx4 v[148:151], v[172:173], off
	s_waitcnt vmcnt(7)
	v_pk_mul_f32 v[152:153], v[152:153], v[112:113] op_sel_hi:[1,0]
	v_pk_mul_f32 v[154:155], v[154:155], v[112:113] op_sel_hi:[1,0]
	ds_write_b128 v60, v[152:155] offset:3264
	v_lshl_add_u64 v[138:139], v[44:45], 0, s[54:55]
	global_load_dwordx4 v[152:155], v[138:139], off
	s_waitcnt vmcnt(7)
	v_pk_mul_f32 v[156:157], v[156:157], v[114:115] op_sel_hi:[1,0]
	v_pk_mul_f32 v[158:159], v[158:159], v[114:115] op_sel_hi:[1,0]
	ds_write_b128 v60, v[156:159] offset:4352
	v_lshl_add_u64 v[172:173], v[42:43], 0, s[54:55]
	global_load_dwordx4 v[156:159], v[172:173], off
	s_waitcnt vmcnt(7)
	v_pk_mul_f32 v[160:161], v[160:161], v[116:117] op_sel_hi:[1,0]
	v_pk_mul_f32 v[162:163], v[162:163], v[116:117] op_sel_hi:[1,0]
	ds_write_b128 v60, v[160:163] offset:5440
	v_lshl_add_u64 v[138:139], v[40:41], 0, s[54:55]
	global_load_dwordx4 v[160:163], v[138:139], off
	s_waitcnt vmcnt(7)
	v_pk_mul_f32 v[164:165], v[164:165], v[118:119] op_sel_hi:[1,0]
	v_pk_mul_f32 v[166:167], v[166:167], v[118:119] op_sel_hi:[1,0]
	ds_write_b128 v60, v[164:167] offset:6528
	v_lshl_add_u64 v[172:173], v[38:39], 0, s[54:55]
	global_load_dwordx4 v[164:167], v[172:173], off
	s_waitcnt vmcnt(7)
	v_pk_mul_f32 v[168:169], v[168:169], v[120:121] op_sel_hi:[1,0]
	v_pk_mul_f32 v[170:171], v[170:171], v[120:121] op_sel_hi:[1,0]
	ds_write_b128 v60, v[168:171] offset:7616
	v_lshl_add_u64 v[138:139], v[34:35], 0, s[54:55]
	global_load_dwordx4 v[168:171], v[138:139], off
	s_add_u32 s54, s54, 0x58000
	s_addc_u32 s55, s55, 0
	s_waitcnt vmcnt(7)
	v_pk_mul_f32 v[140:141], v[140:141], v[122:123] op_sel_hi:[1,0]
	v_pk_mul_f32 v[142:143], v[142:143], v[122:123] op_sel_hi:[1,0]
	ds_write_b128 v60, v[140:143] offset:8704
	s_waitcnt vmcnt(6)
	v_pk_mul_f32 v[144:145], v[144:145], v[124:125] op_sel_hi:[1,0]
	v_pk_mul_f32 v[146:147], v[146:147], v[124:125] op_sel_hi:[1,0]
	ds_write_b128 v60, v[144:147] offset:9792
	s_waitcnt vmcnt(5)
	v_pk_mul_f32 v[148:149], v[148:149], v[126:127] op_sel_hi:[1,0]
	v_pk_mul_f32 v[150:151], v[150:151], v[126:127] op_sel_hi:[1,0]
	ds_write_b128 v60, v[148:151] offset:10880
	s_waitcnt vmcnt(4)
	v_pk_mul_f32 v[152:153], v[152:153], v[240:241] op_sel_hi:[1,0]
	v_pk_mul_f32 v[154:155], v[154:155], v[240:241] op_sel_hi:[1,0]
	ds_write_b128 v60, v[152:155] offset:11968
	s_waitcnt vmcnt(3)
	v_pk_mul_f32 v[156:157], v[156:157], v[242:243] op_sel_hi:[1,0]
	v_pk_mul_f32 v[158:159], v[158:159], v[242:243] op_sel_hi:[1,0]
	ds_write_b128 v60, v[156:159] offset:13056
	s_waitcnt vmcnt(2)
	v_pk_mul_f32 v[160:161], v[160:161], v[244:245] op_sel_hi:[1,0]
	v_pk_mul_f32 v[162:163], v[162:163], v[244:245] op_sel_hi:[1,0]
	ds_write_b128 v60, v[160:163] offset:14144
	s_waitcnt vmcnt(1)
	v_pk_mul_f32 v[164:165], v[164:165], v[246:247] op_sel_hi:[1,0]
	v_pk_mul_f32 v[166:167], v[166:167], v[246:247] op_sel_hi:[1,0]
	ds_write_b128 v60, v[164:167] offset:15232
	s_waitcnt vmcnt(0)
	v_pk_mul_f32 v[168:169], v[168:169], v[248:249] op_sel_hi:[1,0]
	v_pk_mul_f32 v[170:171], v[170:171], v[248:249] op_sel_hi:[1,0]
	ds_write_b128 v60, v[168:171] offset:16320
	v_add_u32_e32 v60, 0x4400, v60
	s_cmp_lg_u32 s54, 0xb0000
	s_branch .LBB0_445

; #define LAS __attribute__((address_space(3)))
;     if (ldk == 0) ldk = K;
;     const int c4 = lane & 15, kr = lane >> 4;
; #pragma unroll 8
;     for (int i = 0; i < 16; ++i) { const int kk = 4 * i + kr; const float gs = gain ? gain[k0 + kk] : 1.f; const f32x4 v = *(const f32x4*)(W + (size_t)(k0 + kk) * N + n0 + 4 * c4); *(LAS f32x4*)(scr + kk * 68 + 4 * c4) = v * gs; }
;     asm volatile("s_waitcnt lgkmcnt(0)" ::: "memory");
.LBB0_450:
	v_add_u32_e32 v44, s14, v40
	v_cndmask_b32_e64 v128, 0, 1, s[54:55]
	v_ashrrev_i32_e32 v45, 31, v44
	v_mov_b32_e32 v106, 1.0
	v_mov_b32_e32 v108, 1.0
	v_mov_b32_e32 v110, 1.0
	v_mov_b32_e32 v112, 1.0
	v_mov_b32_e32 v114, 1.0
	v_mov_b32_e32 v116, 1.0
	v_mov_b32_e32 v118, 1.0
	v_mov_b32_e32 v120, 1.0
	v_mov_b32_e32 v122, 1.0
	v_mov_b32_e32 v124, 1.0
	v_mov_b32_e32 v126, 1.0
	v_mov_b32_e32 v240, 1.0
	v_mov_b32_e32 v242, 1.0
	v_mov_b32_e32 v244, 1.0
	v_mov_b32_e32 v246, 1.0
	v_mov_b32_e32 v248, 1.0
	v_cmp_ne_u32_e64 s[40:41], 1, v128
	s_andn2_b64 vcc, exec, s[54:55]
	s_cbranch_vccnz .Lpw_ng_450
	v_lshl_add_u64 v[172:173], v[44:45], 2, s[52:53]
	global_load_dword v106, v[172:173], off
	global_load_dword v108, v[42:43], off offset:-96
	global_load_dword v110, v[42:43], off offset:-80
	global_load_dword v112, v[42:43], off offset:-64
	global_load_dword v114, v[42:43], off offset:-48
	global_load_dword v116, v[42:43], off offset:-32
	global_load_dword v118, v[42:43], off offset:-16
	global_load_dword v120, v[42:43], off
	global_load_dword v122, v[172:173], off offset:128
	v_lshl_add_u64 v[138:139], v[42:43], 0, s[34:35]
	global_load_dword v124, v[138:139], off offset:-96
	global_load_dword v126, v[138:139], off offset:-80
	global_load_dword v240, v[138:139], off offset:-64
	global_load_dword v242, v[138:139], off offset:-48
	global_load_dword v244, v[138:139], off offset:-32
	global_load_dword v246, v[138:139], off offset:-16
	global_load_dword v248, v[138:139], off
.Lpw_ng_450:
	v_mad_i64_i32 v[140:141], s[56:57], v44, s66, v[38:39]
	global_load_dwordx4 v[140:143], v[140:141], off
	v_add_u32_e32 v128, 4, v44
	v_mad_i64_i32 v[144:145], s[56:57], v128, s66, v[38:39]
	global_load_dwordx4 v[144:147], v[144:145], off
	v_add_u32_e32 v128, 8, v44
	v_mad_i64_i32 v[148:149], s[56:57], v128, s66, v[38:39]
	global_load_dwordx4 v[148:151], v[148:149], off
	v_add_u32_e32 v128, 12, v44
	v_mad_i64_i32 v[152:153], s[56:57], v128, s66, v[38:39]
	global_load_dwordx4 v[152:155], v[152:153], off
	v_add_u32_e32 v128, 16, v44
	v_mad_i64_i32 v[156:157], s[56:57], v128, s66, v[38:39]
	global_load_dwordx4 v[156:159], v[156:157], off
	v_add_u32_e32 v128, 20, v44
	v_mad_i64_i32 v[160:161], s[56:57], v128, s66, v[38:39]
	global_load_dwordx4 v[160:163], v[160:161], off
	v_add_u32_e32 v128, 24, v44
	v_mad_i64_i32 v[164:165], s[56:57], v128, s66, v[38:39]
	global_load_dwordx4 v[164:167], v[164:165], off
	v_add_u32_e32 v128, 28, v44
	v_mad_i64_i32 v[168:169], s[56:57], v128, s66, v[38:39]
	global_load_dwordx4 v[168:171], v[168:169], off
	v_lshl_add_u64 v[42:43], v[42:43], 0, s[34:35]
	v_lshl_add_u64 v[42:43], v[42:43], 0, s[34:35]
	s_waitcnt vmcnt(7)
	v_pk_mul_f32 v[140:141], v[140:141], v[106:107] op_sel_hi:[1,0]
	v_pk_mul_f32 v[142:143], v[142:143], v[106:107] op_sel_hi:[1,0]
	ds_write_b128 v33, v[140:143] offset:0
	v_add_u32_e32 v128, 32, v44
	v_mad_i64_i32 v[172:173], s[56:57], v128, s66, v[38:39]
	global_load_dwordx4 v[140:143], v[172:173], off
	s_waitcnt vmcnt(7)
	v_pk_mul_f32 v[144:145], v[144:145], v[108:109] op_sel_hi:[1,0]
	v_pk_mul_f32 v[146:147], v[146:147], v[108:109] op_sel_hi:[1,0]
	ds_write_b128 v33, v[144:147] offset:1088
	v_add_u32_e32 v128, 36, v44
	v_mad_i64_i32 v[138:139], s[56:57], v128, s66, v[38:39]
	global_load_dwordx4 v[144:147], v[138:139], off
	s_waitcnt vmcnt(7)
	v_pk_mul_f32 v[148:149], v[148:149], v[110:111] op_sel_hi:[1,0]
	v_pk_mul_f32 v[150:151], v[150:151], v[110:111] op_sel_hi:[1,0]
	ds_write_b128 v33, v[148:151] offset:2176
	v_add_u32_e32 v128, 40, v44
	v_mad_i64_i32 v[172:173], s[56:57], v128, s66, v[38:39]
	global_load_dwordx4 v[148:151], v[172:173], off
	s_waitcnt vmcnt(7)
	v_pk_mul_f32 v[152:153], v[152:153], v[112:113] op_sel_hi:[1,0]
	v_pk_mul_f32 v[154:155], v[154:155], v[112:113] op_sel_hi:[1,0]
	ds_write_b128 v33, v[152:155] offset:3264
	v_add_u32_e32 v128, 44, v44
	v_mad_i64_i32 v[138:139], s[56:57], v128, s66, v[38:39]
	global_load_dwordx4 v[152:155], v[138:139], off
	s_waitcnt vmcnt(7)
	v_pk_mul_f32 v[156:157], v[156:157], v[114:115] op_sel_hi:[1,0]
	v_pk_mul_f32 v[158:159], v[158:159], v[114:115] op_sel_hi:[1,0]
	ds_write_b128 v33, v[156:159] offset:4352
	v_add_u32_e32 v128, 48, v44
	v_mad_i64_i32 v[172:173], s[56:57], v128, s66, v[38:39]
	global_load_dwordx4 v[156:159], v[172:173], off
	s_waitcnt vmcnt(7)
	v_pk_mul_f32 v[160:161], v[160:161], v[116:117] op_sel_hi:[1,0]
	v_pk_mul_f32 v[162:163], v[162:163], v[116:117] op_sel_hi:[1,0]
	ds_write_b128 v33, v[160:163] offset:5440
	v_add_u32_e32 v128, 52, v44
	v_mad_i64_i32 v[138:139], s[56:57], v128, s66, v[38:39]
	global_load_dwordx4 v[160:163], v[138:139], off
	s_waitcnt vmcnt(7)
	v_pk_mul_f32 v[164:165], v[164:165], v[118:119] op_sel_hi:[1,0]
	v_pk_mul_f32 v[166:167], v[166:167], v[118:119] op_sel_hi:[1,0]
	ds_write_b128 v33, v[164:167] offset:6528
	v_add_u32_e32 v128, 56, v44
	v_mad_i64_i32 v[172:173], s[56:57], v128, s66, v[38:39]
	global_load_dwordx4 v[164:167], v[172:173], off
	s_waitcnt vmcnt(7)
	v_pk_mul_f32 v[168:169], v[168:169], v[120:121] op_sel_hi:[1,0]
	v_pk_mul_f32 v[170:171], v[170:171], v[120:121] op_sel_hi:[1,0]
	ds_write_b128 v33, v[168:171] offset:7616
	v_add_u32_e32 v128, 60, v44
	v_mad_i64_i32 v[138:139], s[56:57], v128, s66, v[38:39]
	global_load_dwordx4 v[168:171], v[138:139], off
	s_add_i32 s14, s14, 64
	s_waitcnt vmcnt(7)
	v_pk_mul_f32 v[140:141], v[140:141], v[122:123] op_sel_hi:[1,0]
	v_pk_mul_f32 v[142:143], v[142:143], v[122:123] op_sel_hi:[1,0]
	ds_write_b128 v33, v[140:143] offset:8704
	s_waitcnt vmcnt(6)
	v_pk_mul_f32 v[144:145], v[144:145], v[124:125] op_sel_hi:[1,0]
	v_pk_mul_f32 v[146:147], v[146:147], v[124:125] op_sel_hi:[1,0]
	ds_write_b128 v33, v[144:147] offset:9792
	s_waitcnt vmcnt(5)
	v_pk_mul_f32 v[148:149], v[148:149], v[126:127] op_sel_hi:[1,0]
	v_pk_mul_f32 v[150:151], v[150:151], v[126:127] op_sel_hi:[1,0]
	ds_write_b128 v33, v[148:151] offset:10880
	s_waitcnt vmcnt(4)
	v_pk_mul_f32 v[152:153], v[152:153], v[240:241] op_sel_hi:[1,0]
	v_pk_mul_f32 v[154:155], v[154:155], v[240:241] op_sel_hi:[1,0]
	ds_write_b128 v33, v[152:155] offset:11968
	s_waitcnt vmcnt(3)
	v_pk_mul_f32 v[156:157], v[156:157], v[242:243] op_sel_hi:[1,0]
	v_pk_mul_f32 v[158:159], v[158:159], v[242:243] op_sel_hi:[1,0]
	ds_write_b128 v33, v[156:159] offset:13056
	s_waitcnt vmcnt(2)
	v_pk_mul_f32 v[160:161], v[160:161], v[244:245] op_sel_hi:[1,0]
	v_pk_mul_f32 v[162:163], v[162:163], v[244:245] op_sel_hi:[1,0]
	ds_write_b128 v33, v[160:163] offset:14144
	s_waitcnt vmcnt(1)
	v_pk_mul_f32 v[164:165], v[164:165], v[246:247] op_sel_hi:[1,0]
	v_pk_mul_f32 v[166:167], v[166:167], v[246:247] op_sel_hi:[1,0]
	ds_write_b128 v33, v[164:167] offset:15232
	s_waitcnt vmcnt(0)
	v_pk_mul_f32 v[168:169], v[168:169], v[248:249] op_sel_hi:[1,0]
	v_pk_mul_f32 v[170:171], v[170:171], v[248:249] op_sel_hi:[1,0]
	ds_write_b128 v33, v[168:171] offset:16320
	v_add_u32_e32 v33, 0x4400, v33
	s_cmp_lg_u32 s14, 64
	s_branch .LBB0_323

; #define LAS __attribute__((address_space(3)))
;     if (ldk == 0) ldk = K;
;     const int c4 = lane & 15, kr = lane >> 4;
; #pragma unroll 8
;     for (int i = 0; i < 16; ++i) { const int kk = 4 * i + kr; const float gs = gain ? gain[k0 + kk] : 1.f; const f32x4 v = *(const f32x4*)(W + (size_t)(k0 + kk) * N + n0 + 4 * c4); *(LAS f32x4*)(scr + kk * 68 + 4 * c4) = v * gs; }
;     asm volatile("s_waitcnt lgkmcnt(0)" ::: "memory");
.LBB0_477:
	v_cndmask_b32_e64 v128, 0, 1, s[70:71]
	v_mov_b32_e32 v106, 1.0
	v_mov_b32_e32 v108, 1.0
	v_mov_b32_e32 v110, 1.0
	v_mov_b32_e32 v112, 1.0
	v_mov_b32_e32 v114, 1.0
	v_mov_b32_e32 v116, 1.0
	v_mov_b32_e32 v118, 1.0
	v_mov_b32_e32 v120, 1.0
	v_mov_b32_e32 v122, 1.0
	v_mov_b32_e32 v124, 1.0
	v_mov_b32_e32 v126, 1.0
	v_mov_b32_e32 v240, 1.0
	v_mov_b32_e32 v242, 1.0
	v_mov_b32_e32 v244, 1.0
	v_mov_b32_e32 v246, 1.0
	v_mov_b32_e32 v248, 1.0
	v_cmp_ne_u32_e64 s[40:41], 1, v128
	s_andn2_b64 vcc, exec, s[70:71]
	s_cbranch_vccnz .Lpw_ng_477
	v_lshl_add_u64 v[172:173], v[38:39], 0, s[50:51]
	global_load_dword v106, v[172:173], off
	v_lshl_add_u64 v[138:139], v[22:23], 0, s[50:51]
	global_load_dword v108, v[138:139], off offset:16
	global_load_dword v110, v[138:139], off offset:32
	global_load_dword v112, v[138:139], off offset:48
	global_load_dword v114, v[138:139], off offset:64
	global_load_dword v116, v[138:139], off offset:80
	global_load_dword v118, v[138:139], off offset:96
	global_load_dword v120, v[138:139], off offset:112
	v_lshl_add_u64 v[172:173], v[172:173], 0, s[34:35]
	global_load_dword v122, v[172:173], off
	v_lshl_add_u64 v[138:139], v[138:139], 0, s[34:35]
	global_load_dword v124, v[138:139], off offset:16
	global_load_dword v126, v[138:139], off offset:32
	global_load_dword v240, v[138:139], off offset:48
	global_load_dword v242, v[138:139], off offset:64
	global_load_dword v244, v[138:139], off offset:80
	global_load_dword v246, v[138:139], off offset:96
	global_load_dword v248, v[138:139], off offset:112
.Lpw_ng_477:
	v_lshl_add_u64 v[140:141], v[36:37], 0, s[68:69]
	global_load_dwordx4 v[140:143], v[140:141], off
	v_lshl_add_u64 v[144:145], v[34:35], 0, s[68:69]
	global_load_dwordx4 v[144:147], v[144:145], off
	v_lshl_add_u64 v[148:149], v[32:33], 0, s[68:69]
	global_load_dwordx4 v[148:151], v[148:149], off
	v_lshl_add_u64 v[152:153], v[30:31], 0, s[68:69]
	global_load_dwordx4 v[152:155], v[152:153], off
	v_lshl_add_u64 v[156:157], v[28:29], 0, s[68:69]
	global_load_dwordx4 v[156:159], v[156:157], off
	v_lshl_add_u64 v[160:161], v[26:27], 0, s[68:69]
	global_load_dwordx4 v[160:163], v[160:161], off
	v_lshl_add_u64 v[164:165], v[24:25], 0, s[68:69]
	global_load_dwordx4 v[164:167], v[164:165], off
	v_lshl_add_u64 v[168:169], v[20:21], 0, s[68:69]
	global_load_dwordx4 v[168:171], v[168:169], off
	s_add_u32 s68, s68, 0x110000
	s_addc_u32 s69, s69, 0
	v_lshl_add_u64 v[22:23], v[22:23], 0, s[34:35]
	v_lshl_add_u64 v[38:39], v[38:39], 0, s[34:35]
	v_lshl_add_u64 v[22:23], v[22:23], 0, s[34:35]
	v_lshl_add_u64 v[38:39], v[38:39], 0, s[34:35]
	s_waitcnt vmcnt(7)
	v_pk_mul_f32 v[140:141], v[140:141], v[106:107] op_sel_hi:[1,0]
	v_pk_mul_f32 v[142:143], v[142:143], v[106:107] op_sel_hi:[1,0]
	ds_write_b128 v64, v[140:143] offset:0
	v_lshl_add_u64 v[172:173], v[36:37], 0, s[68:69]
	global_load_dwordx4 v[140:143], v[172:173], off
	s_waitcnt vmcnt(7)
	v_pk_mul_f32 v[144:145], v[144:145], v[108:109] op_sel_hi:[1,0]
	v_pk_mul_f32 v[146:147], v[146:147], v[108:109] op_sel_hi:[1,0]
	ds_write_b128 v64, v[144:147] offset:1088
	v_lshl_add_u64 v[138:139], v[34:35], 0, s[68:69]
	global_load_dwordx4 v[144:147], v[138:139], off
	s_waitcnt vmcnt(7)
	v_pk_mul_f32 v[148:149], v[148:149], v[110:111] op_sel_hi:[1,0]
	v_pk_mul_f32 v[150:151], v[150:151], v[110:111] op_sel_hi:[1,0]
	ds_write_b128 v64, v[148:151] offset:2176
	v_lshl_add_u64 v[172:173], v[32:33], 0, s[68:69]
	global_load_dwordx4 v[148:151], v[172:173], off
	s_waitcnt vmcnt(7)
	v_pk_mul_f32 v[152:153], v[152:153], v[112:113] op_sel_hi:[1,0]
	v_pk_mul_f32 v[154:155], v[154:155], v[112:113] op_sel_hi:[1,0]
	ds_write_b128 v64, v[152:155] offset:3264
	v_lshl_add_u64 v[138:139], v[30:31], 0, s[68:69]
	global_load_dwordx4 v[152:155], v[138:139], off
	s_waitcnt vmcnt(7)
	v_pk_mul_f32 v[156:157], v[156:157], v[114:115] op_sel_hi:[1,0]
	v_pk_mul_f32 v[158:159], v[158:159], v[114:115] op_sel_hi:[1,0]
	ds_write_b128 v64, v[156:159] offset:4352
	v_lshl_add_u64 v[172:173], v[28:29], 0, s[68:69]
	global_load_dwordx4 v[156:159], v[172:173], off
	s_waitcnt vmcnt(7)
	v_pk_mul_f32 v[160:161], v[160:161], v[116:117] op_sel_hi:[1,0]
	v_pk_mul_f32 v[162:163], v[162:163], v[116:117] op_sel_hi:[1,0]
	ds_write_b128 v64, v[160:163] offset:5440
	v_lshl_add_u64 v[138:139], v[26:27], 0, s[68:69]
	global_load_dwordx4 v[160:163], v[138:139], off
	s_waitcnt vmcnt(7)
	v_pk_mul_f32 v[164:165], v[164:165], v[118:119] op_sel_hi:[1,0]
	v_pk_mul_f32 v[166:167], v[166:167], v[118:119] op_sel_hi:[1,0]
	ds_write_b128 v64, v[164:167] offset:6528
	v_lshl_add_u64 v[172:173], v[24:25], 0, s[68:69]
	global_load_dwordx4 v[164:167], v[172:173], off
	s_waitcnt vmcnt(7)
	v_pk_mul_f32 v[168:169], v[168:169], v[120:121] op_sel_hi:[1,0]
	v_pk_mul_f32 v[170:171], v[170:171], v[120:121] op_sel_hi:[1,0]
	ds_write_b128 v64, v[168:171] offset:7616
	v_lshl_add_u64 v[138:139], v[20:21], 0, s[68:69]
	global_load_dwordx4 v[168:171], v[138:139], off
	s_add_u32 s68, s68, 0x110000
	s_addc_u32 s69, s69, 0
	s_waitcnt vmcnt(7)
	v_pk_mul_f32 v[140:141], v[140:141], v[122:123] op_sel_hi:[1,0]
	v_pk_mul_f32 v[142:143], v[142:143], v[122:123] op_sel_hi:[1,0]
	ds_write_b128 v64, v[140:143] offset:8704
	s_waitcnt vmcnt(6)
	v_pk_mul_f32 v[144:145], v[144:145], v[124:125] op_sel_hi:[1,0]
	v_pk_mul_f32 v[146:147], v[146:147], v[124:125] op_sel_hi:[1,0]
	ds_write_b128 v64, v[144:147] offset:9792
	s_waitcnt vmcnt(5)
	v_pk_mul_f32 v[148:149], v[148:149], v[126:127] op_sel_hi:[1,0]
	v_pk_mul_f32 v[150:151], v[150:151], v[126:127] op_sel_hi:[1,0]
	ds_write_b128 v64, v[148:151] offset:10880
	s_waitcnt vmcnt(4)
	v_pk_mul_f32 v[152:153], v[152:153], v[240:241] op_sel_hi:[1,0]
	v_pk_mul_f32 v[154:155], v[154:155], v[240:241] op_sel_hi:[1,0]
	ds_write_b128 v64, v[152:155] offset:11968
	s_waitcnt vmcnt(3)
	v_pk_mul_f32 v[156:157], v[156:157], v[242:243] op_sel_hi:[1,0]
	v_pk_mul_f32 v[158:159], v[158:159], v[242:243] op_sel_hi:[1,0]
	ds_write_b128 v64, v[156:159] offset:13056
	s_waitcnt vmcnt(2)
	v_pk_mul_f32 v[160:161], v[160:161], v[244:245] op_sel_hi:[1,0]
	v_pk_mul_f32 v[162:163], v[162:163], v[244:245] op_sel_hi:[1,0]
	ds_write_b128 v64, v[160:163] offset:14144
	s_waitcnt vmcnt(1)
	v_pk_mul_f32 v[164:165], v[164:165], v[246:247] op_sel_hi:[1,0]
	v_pk_mul_f32 v[166:167], v[166:167], v[246:247] op_sel_hi:[1,0]
	ds_write_b128 v64, v[164:167] offset:15232
	s_waitcnt vmcnt(0)
	v_pk_mul_f32 v[168:169], v[168:169], v[248:249] op_sel_hi:[1,0]
	v_pk_mul_f32 v[170:171], v[170:171], v[248:249] op_sel_hi:[1,0]
	ds_write_b128 v64, v[168:171] offset:16320
	v_add_u32_e32 v64, 0x4400, v64
	s_cmp_lg_u32 s68, 0x220000
	s_branch .LBB0_493

; #define LAS __attribute__((address_space(3)))
;     if (ldk == 0) ldk = K;
;     const int c4 = lane & 15, kr = lane >> 4;
; #pragma unroll 8
;     for (int i = 0; i < 16; ++i) { const int kk = 4 * i + kr; const float gs = gain ? gain[k0 + kk] : 1.f; const f32x4 v = *(const f32x4*)(W + (size_t)(k0 + kk) * N + n0 + 4 * c4); *(LAS f32x4*)(scr + kk * 68 + 4 * c4) = v * gs; }
;     asm volatile("s_waitcnt lgkmcnt(0)" ::: "memory");
.LBB0_502:
	v_cndmask_b32_e64 v128, 0, 1, s[58:59]
	v_mov_b32_e32 v106, 1.0
	v_mov_b32_e32 v108, 1.0
	v_mov_b32_e32 v110, 1.0
	v_mov_b32_e32 v112, 1.0
	v_mov_b32_e32 v114, 1.0
	v_mov_b32_e32 v116, 1.0
	v_mov_b32_e32 v118, 1.0
	v_mov_b32_e32 v120, 1.0
	v_mov_b32_e32 v122, 1.0
	v_mov_b32_e32 v124, 1.0
	v_mov_b32_e32 v126, 1.0
	v_mov_b32_e32 v240, 1.0
	v_mov_b32_e32 v242, 1.0
	v_mov_b32_e32 v244, 1.0
	v_mov_b32_e32 v246, 1.0
	v_mov_b32_e32 v248, 1.0
	v_cmp_ne_u32_e64 s[40:41], 1, v128
	s_andn2_b64 vcc, exec, s[58:59]
	s_cbranch_vccnz .Lpw_ng_502
	v_lshl_add_u64 v[172:173], v[38:39], 0, s[50:51]
	global_load_dword v106, v[172:173], off
	v_lshl_add_u64 v[138:139], v[22:23], 0, s[50:51]
	global_load_dword v108, v[138:139], off offset:16
	global_load_dword v110, v[138:139], off offset:32
	global_load_dword v112, v[138:139], off offset:48
	global_load_dword v114, v[138:139], off offset:64
	global_load_dword v116, v[138:139], off offset:80
	global_load_dword v118, v[138:139], off offset:96
	global_load_dword v120, v[138:139], off offset:112
	v_lshl_add_u64 v[172:173], v[172:173], 0, s[34:35]
	global_load_dword v122, v[172:173], off
	v_lshl_add_u64 v[138:139], v[138:139], 0, s[34:35]
	global_load_dword v124, v[138:139], off offset:16
	global_load_dword v126, v[138:139], off offset:32
	global_load_dword v240, v[138:139], off offset:48
	global_load_dword v242, v[138:139], off offset:64
	global_load_dword v244, v[138:139], off offset:80
	global_load_dword v246, v[138:139], off offset:96
	global_load_dword v248, v[138:139], off offset:112
.Lpw_ng_502:
	v_lshl_add_u64 v[140:141], v[36:37], 0, s[56:57]
	global_load_dwordx4 v[140:143], v[140:141], off
	v_lshl_add_u64 v[144:145], v[34:35], 0, s[56:57]
	global_load_dwordx4 v[144:147], v[144:145], off
	v_lshl_add_u64 v[148:149], v[32:33], 0, s[56:57]
	global_load_dwordx4 v[148:151], v[148:149], off
	v_lshl_add_u64 v[152:153], v[30:31], 0, s[56:57]
	global_load_dwordx4 v[152:155], v[152:153], off
	v_lshl_add_u64 v[156:157], v[28:29], 0, s[56:57]
	global_load_dwordx4 v[156:159], v[156:157], off
	v_lshl_add_u64 v[160:161], v[26:27], 0, s[56:57]
	global_load_dwordx4 v[160:163], v[160:161], off
	v_lshl_add_u64 v[164:165], v[24:25], 0, s[56:57]
	global_load_dwordx4 v[164:167], v[164:165], off
	v_lshl_add_u64 v[168:169], v[20:21], 0, s[56:57]
	global_load_dwordx4 v[168:171], v[168:169], off
	s_add_u32 s56, s56, 0x58000
	s_addc_u32 s57, s57, 0
	v_lshl_add_u64 v[22:23], v[22:23], 0, s[34:35]
	v_lshl_add_u64 v[38:39], v[38:39], 0, s[34:35]
	v_lshl_add_u64 v[22:23], v[22:23], 0, s[34:35]
	v_lshl_add_u64 v[38:39], v[38:39], 0, s[34:35]
	s_waitcnt vmcnt(7)
	v_pk_mul_f32 v[140:141], v[140:141], v[106:107] op_sel_hi:[1,0]
	v_pk_mul_f32 v[142:143], v[142:143], v[106:107] op_sel_hi:[1,0]
	ds_write_b128 v65, v[140:143] offset:0
	v_lshl_add_u64 v[172:173], v[36:37], 0, s[56:57]
	global_load_dwordx4 v[140:143], v[172:173], off
	s_waitcnt vmcnt(7)
	v_pk_mul_f32 v[144:145], v[144:145], v[108:109] op_sel_hi:[1,0]
	v_pk_mul_f32 v[146:147], v[146:147], v[108:109] op_sel_hi:[1,0]
	ds_write_b128 v65, v[144:147] offset:1088
	v_lshl_add_u64 v[138:139], v[34:35], 0, s[56:57]
	global_load_dwordx4 v[144:147], v[138:139], off
	s_waitcnt vmcnt(7)
	v_pk_mul_f32 v[148:149], v[148:149], v[110:111] op_sel_hi:[1,0]
	v_pk_mul_f32 v[150:151], v[150:151], v[110:111] op_sel_hi:[1,0]
	ds_write_b128 v65, v[148:151] offset:2176
	v_lshl_add_u64 v[172:173], v[32:33], 0, s[56:57]
	global_load_dwordx4 v[148:151], v[172:173], off
	s_waitcnt vmcnt(7)
	v_pk_mul_f32 v[152:153], v[152:153], v[112:113] op_sel_hi:[1,0]
	v_pk_mul_f32 v[154:155], v[154:155], v[112:113] op_sel_hi:[1,0]
	ds_write_b128 v65, v[152:155] offset:3264
	v_lshl_add_u64 v[138:139], v[30:31], 0, s[56:57]
	global_load_dwordx4 v[152:155], v[138:139], off
	s_waitcnt vmcnt(7)
	v_pk_mul_f32 v[156:157], v[156:157], v[114:115] op_sel_hi:[1,0]
	v_pk_mul_f32 v[158:159], v[158:159], v[114:115] op_sel_hi:[1,0]
	ds_write_b128 v65, v[156:159] offset:4352
	v_lshl_add_u64 v[172:173], v[28:29], 0, s[56:57]
	global_load_dwordx4 v[156:159], v[172:173], off
	s_waitcnt vmcnt(7)
	v_pk_mul_f32 v[160:161], v[160:161], v[116:117] op_sel_hi:[1,0]
	v_pk_mul_f32 v[162:163], v[162:163], v[116:117] op_sel_hi:[1,0]
	ds_write_b128 v65, v[160:163] offset:5440
	v_lshl_add_u64 v[138:139], v[26:27], 0, s[56:57]
	global_load_dwordx4 v[160:163], v[138:139], off
	s_waitcnt vmcnt(7)
	v_pk_mul_f32 v[164:165], v[164:165], v[118:119] op_sel_hi:[1,0]
	v_pk_mul_f32 v[166:167], v[166:167], v[118:119] op_sel_hi:[1,0]
	ds_write_b128 v65, v[164:167] offset:6528
	v_lshl_add_u64 v[172:173], v[24:25], 0, s[56:57]
	global_load_dwordx4 v[164:167], v[172:173], off
	s_waitcnt vmcnt(7)
	v_pk_mul_f32 v[168:169], v[168:169], v[120:121] op_sel_hi:[1,0]
	v_pk_mul_f32 v[170:171], v[170:171], v[120:121] op_sel_hi:[1,0]
	ds_write_b128 v65, v[168:171] offset:7616
	v_lshl_add_u64 v[138:139], v[20:21], 0, s[56:57]
	global_load_dwordx4 v[168:171], v[138:139], off
	s_add_u32 s56, s56, 0x58000
	s_addc_u32 s57, s57, 0
	s_waitcnt vmcnt(7)
	v_pk_mul_f32 v[140:141], v[140:141], v[122:123] op_sel_hi:[1,0]
	v_pk_mul_f32 v[142:143], v[142:143], v[122:123] op_sel_hi:[1,0]
	ds_write_b128 v65, v[140:143] offset:8704
	s_waitcnt vmcnt(6)
	v_pk_mul_f32 v[144:145], v[144:145], v[124:125] op_sel_hi:[1,0]
	v_pk_mul_f32 v[146:147], v[146:147], v[124:125] op_sel_hi:[1,0]
	ds_write_b128 v65, v[144:147] offset:9792
	s_waitcnt vmcnt(5)
	v_pk_mul_f32 v[148:149], v[148:149], v[126:127] op_sel_hi:[1,0]
	v_pk_mul_f32 v[150:151], v[150:151], v[126:127] op_sel_hi:[1,0]
	ds_write_b128 v65, v[148:151] offset:10880
	s_waitcnt vmcnt(4)
	v_pk_mul_f32 v[152:153], v[152:153], v[240:241] op_sel_hi:[1,0]
	v_pk_mul_f32 v[154:155], v[154:155], v[240:241] op_sel_hi:[1,0]
	ds_write_b128 v65, v[152:155] offset:11968
	s_waitcnt vmcnt(3)
	v_pk_mul_f32 v[156:157], v[156:157], v[242:243] op_sel_hi:[1,0]
	v_pk_mul_f32 v[158:159], v[158:159], v[242:243] op_sel_hi:[1,0]
	ds_write_b128 v65, v[156:159] offset:13056
	s_waitcnt vmcnt(2)
	v_pk_mul_f32 v[160:161], v[160:161], v[244:245] op_sel_hi:[1,0]
	v_pk_mul_f32 v[162:163], v[162:163], v[244:245] op_sel_hi:[1,0]
	ds_write_b128 v65, v[160:163] offset:14144
	s_waitcnt vmcnt(1)
	v_pk_mul_f32 v[164:165], v[164:165], v[246:247] op_sel_hi:[1,0]
	v_pk_mul_f32 v[166:167], v[166:167], v[246:247] op_sel_hi:[1,0]
	ds_write_b128 v65, v[164:167] offset:15232
	s_waitcnt vmcnt(0)
	v_pk_mul_f32 v[168:169], v[168:169], v[248:249] op_sel_hi:[1,0]
	v_pk_mul_f32 v[170:171], v[170:171], v[248:249] op_sel_hi:[1,0]
	ds_write_b128 v65, v[168:171] offset:16320
	v_add_u32_e32 v65, 0x4400, v65
	s_cmp_lg_u32 s56, 0xb0000
	s_branch .LBB0_518

; #define LAS __attribute__((address_space(3)))
;     if (ldk == 0) ldk = K;
;     const int c4 = lane & 15, kr = lane >> 4;
; #pragma unroll 8
;     for (int i = 0; i < 16; ++i) { const int kk = 4 * i + kr; const float gs = gain ? gain[k0 + kk] : 1.f; const f32x4 v = *(const f32x4*)(W + (size_t)(k0 + kk) * N + n0 + 4 * c4); *(LAS f32x4*)(scr + kk * 68 + 4 * c4) = v * gs; }
;     asm volatile("s_waitcnt lgkmcnt(0)" ::: "memory");
.LBB0_523:
	v_add_u32_e32 v30, s30, v26
	v_cndmask_b32_e64 v128, 0, 1, s[56:57]
	v_ashrrev_i32_e32 v31, 31, v30
	v_mov_b32_e32 v106, 1.0
	v_mov_b32_e32 v108, 1.0
	v_mov_b32_e32 v110, 1.0
	v_mov_b32_e32 v112, 1.0
	v_mov_b32_e32 v114, 1.0
	v_mov_b32_e32 v116, 1.0
	v_mov_b32_e32 v118, 1.0
	v_mov_b32_e32 v120, 1.0
	v_mov_b32_e32 v122, 1.0
	v_mov_b32_e32 v124, 1.0
	v_mov_b32_e32 v126, 1.0
	v_mov_b32_e32 v240, 1.0
	v_mov_b32_e32 v242, 1.0
	v_mov_b32_e32 v244, 1.0
	v_mov_b32_e32 v246, 1.0
	v_mov_b32_e32 v248, 1.0
	v_cmp_ne_u32_e64 s[40:41], 1, v128
	s_andn2_b64 vcc, exec, s[56:57]
	s_cbranch_vccnz .Lpw_ng_523
	v_lshl_add_u64 v[172:173], v[30:31], 2, s[54:55]
	global_load_dword v106, v[172:173], off
	global_load_dword v108, v[28:29], off offset:-96
	global_load_dword v110, v[28:29], off offset:-80
	global_load_dword v112, v[28:29], off offset:-64
	global_load_dword v114, v[28:29], off offset:-48
	global_load_dword v116, v[28:29], off offset:-32
	global_load_dword v118, v[28:29], off offset:-16
	global_load_dword v120, v[28:29], off
	global_load_dword v122, v[172:173], off offset:128
	v_lshl_add_u64 v[138:139], v[28:29], 0, s[34:35]
	global_load_dword v124, v[138:139], off offset:-96
	global_load_dword v126, v[138:139], off offset:-80
	global_load_dword v240, v[138:139], off offset:-64
	global_load_dword v242, v[138:139], off offset:-48
	global_load_dword v244, v[138:139], off offset:-32
	global_load_dword v246, v[138:139], off offset:-16
	global_load_dword v248, v[138:139], off
.Lpw_ng_523:
	v_mad_i64_i32 v[140:141], s[58:59], v30, s66, v[24:25]
	global_load_dwordx4 v[140:143], v[140:141], off
	v_add_u32_e32 v128, 4, v30
	v_mad_i64_i32 v[144:145], s[58:59], v128, s66, v[24:25]
	global_load_dwordx4 v[144:147], v[144:145], off
	v_add_u32_e32 v128, 8, v30
	v_mad_i64_i32 v[148:149], s[58:59], v128, s66, v[24:25]
	global_load_dwordx4 v[148:151], v[148:149], off
	v_add_u32_e32 v128, 12, v30
	v_mad_i64_i32 v[152:153], s[58:59], v128, s66, v[24:25]
	global_load_dwordx4 v[152:155], v[152:153], off
	v_add_u32_e32 v128, 16, v30
	v_mad_i64_i32 v[156:157], s[58:59], v128, s66, v[24:25]
	global_load_dwordx4 v[156:159], v[156:157], off
	v_add_u32_e32 v128, 20, v30
	v_mad_i64_i32 v[160:161], s[58:59], v128, s66, v[24:25]
	global_load_dwordx4 v[160:163], v[160:161], off
	v_add_u32_e32 v128, 24, v30
	v_mad_i64_i32 v[164:165], s[58:59], v128, s66, v[24:25]
	global_load_dwordx4 v[164:167], v[164:165], off
	v_add_u32_e32 v128, 28, v30
	v_mad_i64_i32 v[168:169], s[58:59], v128, s66, v[24:25]
	global_load_dwordx4 v[168:171], v[168:169], off
	v_lshl_add_u64 v[28:29], v[28:29], 0, s[34:35]
	v_lshl_add_u64 v[28:29], v[28:29], 0, s[34:35]
	s_waitcnt vmcnt(7)
	v_pk_mul_f32 v[140:141], v[140:141], v[106:107] op_sel_hi:[1,0]
	v_pk_mul_f32 v[142:143], v[142:143], v[106:107] op_sel_hi:[1,0]
	ds_write_b128 v19, v[140:143] offset:0
	v_add_u32_e32 v128, 32, v30
	v_mad_i64_i32 v[172:173], s[58:59], v128, s66, v[24:25]
	global_load_dwordx4 v[140:143], v[172:173], off
	s_waitcnt vmcnt(7)
	v_pk_mul_f32 v[144:145], v[144:145], v[108:109] op_sel_hi:[1,0]
	v_pk_mul_f32 v[146:147], v[146:147], v[108:109] op_sel_hi:[1,0]
	ds_write_b128 v19, v[144:147] offset:1088
	v_add_u32_e32 v128, 36, v30
	v_mad_i64_i32 v[138:139], s[58:59], v128, s66, v[24:25]
	global_load_dwordx4 v[144:147], v[138:139], off
	s_waitcnt vmcnt(7)
	v_pk_mul_f32 v[148:149], v[148:149], v[110:111] op_sel_hi:[1,0]
	v_pk_mul_f32 v[150:151], v[150:151], v[110:111] op_sel_hi:[1,0]
	ds_write_b128 v19, v[148:151] offset:2176
	v_add_u32_e32 v128, 40, v30
	v_mad_i64_i32 v[172:173], s[58:59], v128, s66, v[24:25]
	global_load_dwordx4 v[148:151], v[172:173], off
	s_waitcnt vmcnt(7)
	v_pk_mul_f32 v[152:153], v[152:153], v[112:113] op_sel_hi:[1,0]
	v_pk_mul_f32 v[154:155], v[154:155], v[112:113] op_sel_hi:[1,0]
	ds_write_b128 v19, v[152:155] offset:3264
	v_add_u32_e32 v128, 44, v30
	v_mad_i64_i32 v[138:139], s[58:59], v128, s66, v[24:25]
	global_load_dwordx4 v[152:155], v[138:139], off
	s_waitcnt vmcnt(7)
	v_pk_mul_f32 v[156:157], v[156:157], v[114:115] op_sel_hi:[1,0]
	v_pk_mul_f32 v[158:159], v[158:159], v[114:115] op_sel_hi:[1,0]
	ds_write_b128 v19, v[156:159] offset:4352
	v_add_u32_e32 v128, 48, v30
	v_mad_i64_i32 v[172:173], s[58:59], v128, s66, v[24:25]
	global_load_dwordx4 v[156:159], v[172:173], off
	s_waitcnt vmcnt(7)
	v_pk_mul_f32 v[160:161], v[160:161], v[116:117] op_sel_hi:[1,0]
	v_pk_mul_f32 v[162:163], v[162:163], v[116:117] op_sel_hi:[1,0]
	ds_write_b128 v19, v[160:163] offset:5440
	v_add_u32_e32 v128, 52, v30
	v_mad_i64_i32 v[138:139], s[58:59], v128, s66, v[24:25]
	global_load_dwordx4 v[160:163], v[138:139], off
	s_waitcnt vmcnt(7)
	v_pk_mul_f32 v[164:165], v[164:165], v[118:119] op_sel_hi:[1,0]
	v_pk_mul_f32 v[166:167], v[166:167], v[118:119] op_sel_hi:[1,0]
	ds_write_b128 v19, v[164:167] offset:6528
	v_add_u32_e32 v128, 56, v30
	v_mad_i64_i32 v[172:173], s[58:59], v128, s66, v[24:25]
	global_load_dwordx4 v[164:167], v[172:173], off
	s_waitcnt vmcnt(7)
	v_pk_mul_f32 v[168:169], v[168:169], v[120:121] op_sel_hi:[1,0]
	v_pk_mul_f32 v[170:171], v[170:171], v[120:121] op_sel_hi:[1,0]
	ds_write_b128 v19, v[168:171] offset:7616
	v_add_u32_e32 v128, 60, v30
	v_mad_i64_i32 v[138:139], s[58:59], v128, s66, v[24:25]
	global_load_dwordx4 v[168:171], v[138:139], off
	s_add_i32 s30, s30, 64
	s_waitcnt vmcnt(7)
	v_pk_mul_f32 v[140:141], v[140:141], v[122:123] op_sel_hi:[1,0]
	v_pk_mul_f32 v[142:143], v[142:143], v[122:123] op_sel_hi:[1,0]
	ds_write_b128 v19, v[140:143] offset:8704
	s_waitcnt vmcnt(6)
	v_pk_mul_f32 v[144:145], v[144:145], v[124:125] op_sel_hi:[1,0]
	v_pk_mul_f32 v[146:147], v[146:147], v[124:125] op_sel_hi:[1,0]
	ds_write_b128 v19, v[144:147] offset:9792
	s_waitcnt vmcnt(5)
	v_pk_mul_f32 v[148:149], v[148:149], v[126:127] op_sel_hi:[1,0]
	v_pk_mul_f32 v[150:151], v[150:151], v[126:127] op_sel_hi:[1,0]
	ds_write_b128 v19, v[148:151] offset:10880
	s_waitcnt vmcnt(4)
	v_pk_mul_f32 v[152:153], v[152:153], v[240:241] op_sel_hi:[1,0]
	v_pk_mul_f32 v[154:155], v[154:155], v[240:241] op_sel_hi:[1,0]
	ds_write_b128 v19, v[152:155] offset:11968
	s_waitcnt vmcnt(3)
	v_pk_mul_f32 v[156:157], v[156:157], v[242:243] op_sel_hi:[1,0]
	v_pk_mul_f32 v[158:159], v[158:159], v[242:243] op_sel_hi:[1,0]
	ds_write_b128 v19, v[156:159] offset:13056
	s_waitcnt vmcnt(2)
	v_pk_mul_f32 v[160:161], v[160:161], v[244:245] op_sel_hi:[1,0]
	v_pk_mul_f32 v[162:163], v[162:163], v[244:245] op_sel_hi:[1,0]
	ds_write_b128 v19, v[160:163] offset:14144
	s_waitcnt vmcnt(1)
	v_pk_mul_f32 v[164:165], v[164:165], v[246:247] op_sel_hi:[1,0]
	v_pk_mul_f32 v[166:167], v[166:167], v[246:247] op_sel_hi:[1,0]
	ds_write_b128 v19, v[164:167] offset:15232
	s_waitcnt vmcnt(0)
	v_pk_mul_f32 v[168:169], v[168:169], v[248:249] op_sel_hi:[1,0]
	v_pk_mul_f32 v[170:171], v[170:171], v[248:249] op_sel_hi:[1,0]
	ds_write_b128 v19, v[168:171] offset:16320
	v_add_u32_e32 v19, 0x4400, v19
	s_cmp_lg_u32 s30, 64
	s_branch .LBB0_470
